# phase-0 input row loads marked non-temporal (streamed once; keeps the normalised rows and weights cached for phase 1)
# baseline (speedup 1.0000x reference)
.LBB0_8:
	v_ashrrev_i32_e32 v77, 31, v76
	v_lshlrev_b64 v[18:19], 12, v[76:77]
	v_lshl_add_u64 v[18:19], v[68:69], 0, v[18:19]
	global_load_dwordx4 v[80:83], v[18:19], off nt
	global_load_dwordx4 v[84:87], v[18:19], off offset:16 nt
	global_load_dwordx4 v[88:91], v[18:19], off offset:32 nt
	global_load_dwordx4 v[92:95], v[18:19], off offset:48 nt
	v_add_u32_e32 v70, s33, v76
	v_add_u32_e32 v74, s10, v76
	v_add_u32_e32 v72, s52, v76
	v_min_i32_e32 v18, 0x7fff, v70
	v_min_i32_e32 v20, 0x7fff, v74
	v_min_i32_e32 v22, 0x7fff, v72
	v_ashrrev_i32_e32 v19, 31, v18
	v_ashrrev_i32_e32 v21, 31, v20
	v_ashrrev_i32_e32 v23, 31, v22
	v_lshlrev_b64 v[18:19], 12, v[18:19]
	v_lshlrev_b64 v[20:21], 12, v[20:21]
	v_lshlrev_b64 v[22:23], 12, v[22:23]
	v_lshl_add_u64 v[18:19], v[68:69], 0, v[18:19]
	v_lshl_add_u64 v[20:21], v[68:69], 0, v[20:21]
	v_lshl_add_u64 v[30:31], v[68:69], 0, v[22:23]
	global_load_dwordx4 v[50:53], v[18:19], off offset:48 nt
	global_load_dwordx4 v[54:57], v[18:19], off offset:32 nt
	global_load_dwordx4 v[58:61], v[18:19], off offset:16 nt
	global_load_dwordx4 v[62:65], v[18:19], off nt
	global_load_dwordx4 v[34:37], v[20:21], off offset:48 nt
	global_load_dwordx4 v[38:41], v[20:21], off offset:32 nt
	global_load_dwordx4 v[42:45], v[20:21], off offset:16 nt
	global_load_dwordx4 v[46:49], v[20:21], off nt
	s_nop 0
	global_load_dwordx4 v[18:21], v[30:31], off offset:48 nt
	global_load_dwordx4 v[22:25], v[30:31], off offset:32 nt
	global_load_dwordx4 v[26:29], v[30:31], off offset:16 nt
	s_nop 0
	global_load_dwordx4 v[30:33], v[30:31], off nt
	v_lshlrev_b64 v[76:77], 11, v[76:77]
	v_lshl_add_u64 v[76:77], v[66:67], 0, v[76:77]
	s_waitcnt vmcnt(15)
	v_mov_b32_e32 v98, v81
	s_waitcnt vmcnt(14)
	v_mov_b32_e32 v99, v85
	v_mov_b32_e32 v96, v80
	v_mov_b32_e32 v97, v84
	s_waitcnt vmcnt(13)
	v_mov_b32_e32 v104, v89
	s_waitcnt vmcnt(12)
	v_mov_b32_e32 v105, v93
	v_pk_mul_f32 v[98:99], v[98:99], v[98:99]
	v_mov_b32_e32 v100, v82
	v_mov_b32_e32 v101, v86
	v_mov_b32_e32 v102, v88
	v_mov_b32_e32 v103, v92
	v_pk_mul_f32 v[104:105], v[104:105], v[104:105]
	v_pk_fma_f32 v[96:97], v[96:97], v[96:97], v[98:99]
	v_mov_b32_e32 v106, v83
	v_mov_b32_e32 v107, v87
	v_mov_b32_e32 v108, v90
	v_mov_b32_e32 v109, v94
	v_pk_fma_f32 v[98:99], v[102:103], v[102:103], v[104:105]
	v_pk_fma_f32 v[96:97], v[100:101], v[100:101], v[96:97]
	v_mov_b32_e32 v110, v91
	v_mov_b32_e32 v111, v95
	v_pk_fma_f32 v[98:99], v[108:109], v[108:109], v[98:99]
	v_pk_fma_f32 v[96:97], v[106:107], v[106:107], v[96:97]
	v_pk_fma_f32 v[98:99], v[110:111], v[110:111], v[98:99]
	v_add_f32_e32 v71, v96, v97
	v_add_f32_e32 v71, v71, v98
	v_add_f32_e32 v71, v71, v99
	s_nop 1
	v_add_f32_dpp v71, v71, v71 quad_perm:[1,0,3,2] row_mask:0xf bank_mask:0xf bound_ctrl:1
	s_nop 1
	v_add_f32_dpp v71, v71, v71 quad_perm:[2,3,0,1] row_mask:0xf bank_mask:0xf bound_ctrl:1
	s_nop 1
	v_add_f32_dpp v71, v71, v71 row_half_mirror row_mask:0xf bank_mask:0xf bound_ctrl:1
	s_nop 1
	v_add_f32_dpp v71, v71, v71 row_mirror row_mask:0xf bank_mask:0xf bound_ctrl:1
	s_nop 0
	v_readlane_b32 s14, v71, 16
	v_readlane_b32 s15, v71, 48
	v_readlane_b32 s8, v71, 0
	v_readlane_b32 s9, v71, 32
	v_mov_b32_e32 v96, s14
	v_mov_b32_e32 v97, s15
	v_pk_add_f32 v[96:97], s[8:9], v[96:97]
	s_nop 0
	v_add_f32_e32 v71, v96, v97
	v_fmamk_f32 v71, v71, 0x3a800000, v78
	v_mul_f32_e32 v73, 0x4b800000, v71
	v_cmp_gt_f32_e32 vcc, s12, v71
	s_nop 1
	v_cndmask_b32_e32 v71, v71, v73, vcc
	v_rsq_f32_e32 v71, v71
	s_nop 0
	v_mul_f32_e32 v73, 0x45800000, v71
	v_cndmask_b32_e32 v71, v71, v73, vcc
	v_mul_f32_e32 v73, v80, v71
	v_mul_f32_e32 v75, v81, v71
	v_mul_f32_e32 v79, v82, v71
	v_mul_f32_e32 v80, v83, v71
	v_mul_f32_e32 v81, v84, v71
	v_mul_f32_e32 v82, v85, v71
	v_mul_f32_e32 v83, v86, v71
	v_mul_f32_e32 v84, v87, v71
	v_mul_f32_e32 v85, v88, v71
	v_mul_f32_e32 v87, v90, v71
	v_mul_f32_e32 v73, v2, v73
	v_mul_f32_e32 v86, v89, v71
	v_mul_f32_e32 v88, v91, v71
	v_mul_f32_e32 v89, v92, v71
	v_mul_f32_e32 v75, v3, v75
	v_mul_f32_e32 v92, v5, v80
	v_mul_f32_e32 v82, v7, v82
	v_mul_f32_e32 v83, v8, v83
	v_mul_f32_e32 v84, v9, v84
	v_mul_f32_e32 v85, v10, v85
	v_cvt_pk_bf16_f32 v80, v73, v75
	v_mul_f32_e32 v73, v12, v87
	v_mul_f32_e32 v90, v93, v71
	v_mul_f32_e32 v91, v94, v71
	v_mul_f32_e32 v71, v95, v71
	v_mul_f32_e32 v79, v4, v79
	v_mul_f32_e32 v93, v6, v81
	v_mul_f32_e32 v86, v11, v86
	v_cvt_pk_bf16_f32 v81, v79, v92
	v_cvt_pk_bf16_f32 v82, v93, v82
	v_cvt_pk_bf16_f32 v83, v83, v84
	v_mul_f32_e32 v75, v13, v88
	v_cvt_pk_bf16_f32 v84, v85, v86
	v_cvt_pk_bf16_f32 v85, v73, v75
	v_mul_f32_e32 v73, v14, v89
	v_cmp_gt_i32_e32 vcc, s3, v70
	v_mul_f32_e32 v75, v15, v90
	v_cvt_pk_bf16_f32 v86, v73, v75
	v_mul_f32_e32 v73, v16, v91
	v_mul_f32_e32 v71, v17, v71
	v_cvt_pk_bf16_f32 v87, v73, v71
	global_store_dwordx4 v[76:77], v[80:83], off
	global_store_dwordx4 v[76:77], v[84:87], off offset:16
	s_and_saveexec_b64 s[8:9], vcc
	s_cbranch_execz .Lp0_drain
	s_waitcnt vmcnt(10)
	v_mov_b32_e32 v80, v63
	v_mov_b32_e32 v81, v59
	v_mov_b32_e32 v76, v62
	v_mov_b32_e32 v77, v58
	v_pk_mul_f32 v[80:81], v[80:81], v[80:81]
	v_mov_b32_e32 v82, v55
	v_pk_fma_f32 v[76:77], v[76:77], v[76:77], v[80:81]
	v_mov_b32_e32 v80, v64
	v_mov_b32_e32 v81, v60
	v_pk_fma_f32 v[76:77], v[80:81], v[80:81], v[76:77]
	v_mov_b32_e32 v80, v65
	v_mov_b32_e32 v81, v61
	v_mov_b32_e32 v83, v51
	v_pk_fma_f32 v[76:77], v[80:81], v[80:81], v[76:77]
	v_mov_b32_e32 v80, v54
	v_mov_b32_e32 v81, v50
	v_pk_mul_f32 v[82:83], v[82:83], v[82:83]
	v_add_f32_e32 v71, v76, v77
	v_pk_fma_f32 v[80:81], v[80:81], v[80:81], v[82:83]
	v_mov_b32_e32 v82, v56
	v_mov_b32_e32 v83, v52
	v_pk_fma_f32 v[80:81], v[82:83], v[82:83], v[80:81]
	v_mov_b32_e32 v82, v57
	v_mov_b32_e32 v83, v53
	v_pk_fma_f32 v[80:81], v[82:83], v[82:83], v[80:81]
	s_nop 0
	v_add_f32_e32 v71, v71, v80
	v_add_f32_e32 v71, v71, v81
	s_nop 1
	v_add_f32_dpp v71, v71, v71 quad_perm:[1,0,3,2] row_mask:0xf bank_mask:0xf bound_ctrl:1
	s_nop 1
	v_add_f32_dpp v71, v71, v71 quad_perm:[2,3,0,1] row_mask:0xf bank_mask:0xf bound_ctrl:1
	s_nop 1
	v_add_f32_dpp v71, v71, v71 row_half_mirror row_mask:0xf bank_mask:0xf bound_ctrl:1
	s_nop 1
	v_add_f32_dpp v71, v71, v71 row_mirror row_mask:0xf bank_mask:0xf bound_ctrl:1
	s_nop 0
	v_readlane_b32 s16, v71, 16
	v_readlane_b32 s17, v71, 48
	v_readlane_b32 s14, v71, 0
	v_readlane_b32 s15, v71, 32
	v_mov_b32_e32 v76, s16
	v_mov_b32_e32 v77, s17
	v_pk_add_f32 v[76:77], s[14:15], v[76:77]
	s_nop 0
	v_add_f32_e32 v71, v76, v77
	v_fmamk_f32 v71, v71, 0x3a800000, v78
	v_mul_f32_e32 v73, 0x4b800000, v71
	v_cmp_gt_f32_e32 vcc, s12, v71
	s_nop 1
	v_cndmask_b32_e32 v71, v71, v73, vcc
	v_rsq_f32_e32 v71, v71
	s_nop 0
	v_mul_f32_e32 v73, 0x45800000, v71
	v_cndmask_b32_e32 v71, v71, v73, vcc
	v_mul_f32_e32 v50, v50, v71
	v_mul_f32_e32 v73, v14, v50
	v_mul_f32_e32 v50, v51, v71
	v_mul_f32_e32 v75, v15, v50
	v_mul_f32_e32 v50, v52, v71
	v_mul_f32_e32 v54, v54, v71
	v_mul_f32_e32 v55, v55, v71
	v_mul_f32_e32 v56, v56, v71
	v_mul_f32_e32 v57, v57, v71
	v_mul_f32_e32 v76, v16, v50
	v_mul_f32_e32 v50, v53, v71
	v_mul_f32_e32 v62, v62, v71
	v_mul_f32_e32 v63, v63, v71
	v_mul_f32_e32 v64, v64, v71
	v_mul_f32_e32 v65, v65, v71
	v_mul_f32_e32 v58, v58, v71
	v_mul_f32_e32 v59, v59, v71
	v_mul_f32_e32 v60, v60, v71
	v_mul_f32_e32 v61, v61, v71
	v_mul_f32_e32 v54, v10, v54
	v_mul_f32_e32 v55, v11, v55
	v_mul_f32_e32 v56, v12, v56
	v_mul_f32_e32 v57, v13, v57
	v_mul_f32_e32 v71, v17, v50
	v_mul_f32_e32 v62, v2, v62
	v_mul_f32_e32 v63, v3, v63
	v_mul_f32_e32 v64, v4, v64
	v_mul_f32_e32 v65, v5, v65
	v_mul_f32_e32 v58, v6, v58
	v_mul_f32_e32 v59, v7, v59
	v_mul_f32_e32 v60, v8, v60
	v_mul_f32_e32 v61, v9, v61
	v_cvt_pk_bf16_f32 v50, v62, v63
	v_cvt_pk_bf16_f32 v51, v64, v65
	v_cvt_pk_bf16_f32 v52, v58, v59
	v_cvt_pk_bf16_f32 v53, v60, v61
	v_cvt_pk_bf16_f32 v54, v54, v55
	v_cvt_pk_bf16_f32 v55, v56, v57
	v_cvt_pk_bf16_f32 v56, v73, v75
	v_cvt_pk_bf16_f32 v57, v76, v71
	v_ashrrev_i32_e32 v71, 31, v70
	v_lshlrev_b64 v[58:59], 11, v[70:71]
	v_lshl_add_u64 v[58:59], v[66:67], 0, v[58:59]
	v_cmp_gt_i32_e32 vcc, s3, v74
	global_store_dwordx4 v[58:59], v[50:53], off
	global_store_dwordx4 v[58:59], v[54:57], off offset:16
	s_and_b64 exec, exec, vcc
	s_cbranch_execz .Lp0_drain
	s_waitcnt vmcnt(8)
	v_mov_b32_e32 v52, v47
	v_mov_b32_e32 v53, v43
	v_mov_b32_e32 v50, v46
	v_mov_b32_e32 v51, v42
	v_pk_mul_f32 v[52:53], v[52:53], v[52:53]
	v_mov_b32_e32 v54, v39
	v_pk_fma_f32 v[50:51], v[50:51], v[50:51], v[52:53]
	v_mov_b32_e32 v52, v48
	v_mov_b32_e32 v53, v44
	v_pk_fma_f32 v[50:51], v[52:53], v[52:53], v[50:51]
	v_mov_b32_e32 v52, v49
	v_mov_b32_e32 v53, v45
	v_mov_b32_e32 v55, v35
	v_pk_fma_f32 v[50:51], v[52:53], v[52:53], v[50:51]
	v_mov_b32_e32 v52, v38
	v_mov_b32_e32 v53, v34
	v_pk_mul_f32 v[54:55], v[54:55], v[54:55]
	v_add_f32_e32 v50, v50, v51
	v_pk_fma_f32 v[52:53], v[52:53], v[52:53], v[54:55]
	v_mov_b32_e32 v54, v40
	v_mov_b32_e32 v55, v36
	v_pk_fma_f32 v[52:53], v[54:55], v[54:55], v[52:53]
	v_mov_b32_e32 v54, v41
	v_mov_b32_e32 v55, v37
	v_pk_fma_f32 v[52:53], v[54:55], v[54:55], v[52:53]
	v_ashrrev_i32_e32 v75, 31, v74
	v_add_f32_e32 v50, v50, v52
	v_add_f32_e32 v50, v50, v53
	s_nop 1
	v_add_f32_dpp v50, v50, v50 quad_perm:[1,0,3,2] row_mask:0xf bank_mask:0xf bound_ctrl:1
	s_nop 1
	v_add_f32_dpp v50, v50, v50 quad_perm:[2,3,0,1] row_mask:0xf bank_mask:0xf bound_ctrl:1
	s_nop 1
	v_add_f32_dpp v50, v50, v50 row_half_mirror row_mask:0xf bank_mask:0xf bound_ctrl:1
	s_nop 1
	v_add_f32_dpp v50, v50, v50 row_mirror row_mask:0xf bank_mask:0xf bound_ctrl:1
	s_nop 0
	v_readlane_b32 s16, v50, 16
	v_readlane_b32 s17, v50, 48
	v_readlane_b32 s14, v50, 0
	v_readlane_b32 s15, v50, 32
	v_mov_b32_e32 v50, s16
	v_mov_b32_e32 v51, s17
	v_pk_add_f32 v[50:51], s[14:15], v[50:51]
	s_nop 0
	v_add_f32_e32 v50, v50, v51
	v_fmamk_f32 v50, v50, 0x3a800000, v78
	v_mul_f32_e32 v51, 0x4b800000, v50
	v_cmp_gt_f32_e32 vcc, s12, v50
	s_nop 1
	v_cndmask_b32_e32 v50, v50, v51, vcc
	v_rsq_f32_e32 v50, v50
	s_nop 0
	v_mul_f32_e32 v51, 0x45800000, v50
	v_cndmask_b32_e32 v50, v50, v51, vcc
	v_mul_f32_e32 v34, v34, v50
	v_mul_f32_e32 v51, v14, v34
	v_mul_f32_e32 v34, v35, v50
	v_mul_f32_e32 v42, v42, v50
	v_mul_f32_e32 v43, v43, v50
	v_mul_f32_e32 v52, v15, v34
	v_mul_f32_e32 v34, v36, v50
	v_mul_f32_e32 v46, v46, v50
	v_mul_f32_e32 v47, v47, v50
	v_mul_f32_e32 v48, v48, v50
	v_mul_f32_e32 v49, v49, v50
	v_mul_f32_e32 v42, v6, v42
	v_mul_f32_e32 v43, v7, v43
	v_mul_f32_e32 v53, v16, v34
	v_mul_f32_e32 v34, v37, v50
	v_mul_f32_e32 v46, v2, v46
	v_mul_f32_e32 v47, v3, v47
	v_mul_f32_e32 v48, v4, v48
	v_mul_f32_e32 v49, v5, v49
	v_mul_f32_e32 v44, v44, v50
	v_mul_f32_e32 v45, v45, v50
	v_mul_f32_e32 v38, v38, v50
	v_mul_f32_e32 v39, v39, v50
	v_mul_f32_e32 v40, v40, v50
	v_mul_f32_e32 v41, v41, v50
	v_mul_f32_e32 v50, v17, v34
	v_cvt_pk_bf16_f32 v34, v46, v47
	v_cvt_pk_bf16_f32 v35, v48, v49
	v_cvt_pk_bf16_f32 v36, v42, v43
	v_lshlrev_b64 v[42:43], 11, v[74:75]
	v_mul_f32_e32 v44, v8, v44
	v_mul_f32_e32 v45, v9, v45
	v_mul_f32_e32 v38, v10, v38
	v_mul_f32_e32 v39, v11, v39
	v_mul_f32_e32 v40, v12, v40
	v_mul_f32_e32 v41, v13, v41
	v_cvt_pk_bf16_f32 v37, v44, v45
	v_lshl_add_u64 v[42:43], v[66:67], 0, v[42:43]
	v_cmp_gt_i32_e32 vcc, s3, v72
	v_cvt_pk_bf16_f32 v38, v38, v39
	v_cvt_pk_bf16_f32 v39, v40, v41
	v_cvt_pk_bf16_f32 v40, v51, v52
	v_cvt_pk_bf16_f32 v41, v53, v50
	global_store_dwordx4 v[42:43], v[34:37], off
	global_store_dwordx4 v[42:43], v[38:41], off offset:16
	s_and_b64 exec, exec, vcc
	s_cbranch_execz .Lp0_drain
	s_waitcnt vmcnt(6)
	v_mov_b32_e32 v36, v31
	v_mov_b32_e32 v37, v27
	v_mov_b32_e32 v34, v30
	v_mov_b32_e32 v35, v26
	v_pk_mul_f32 v[36:37], v[36:37], v[36:37]
	v_mov_b32_e32 v38, v23
	v_pk_fma_f32 v[34:35], v[34:35], v[34:35], v[36:37]
	v_mov_b32_e32 v36, v32
	v_mov_b32_e32 v37, v28
	v_pk_fma_f32 v[34:35], v[36:37], v[36:37], v[34:35]
	v_mov_b32_e32 v36, v33
	v_mov_b32_e32 v37, v29
	v_mov_b32_e32 v39, v19
	v_pk_fma_f32 v[34:35], v[36:37], v[36:37], v[34:35]
	v_mov_b32_e32 v36, v22
	v_mov_b32_e32 v37, v18
	v_pk_mul_f32 v[38:39], v[38:39], v[38:39]
	v_add_f32_e32 v34, v34, v35
	v_pk_fma_f32 v[36:37], v[36:37], v[36:37], v[38:39]
	v_mov_b32_e32 v38, v24
	v_mov_b32_e32 v39, v20
	v_pk_fma_f32 v[36:37], v[38:39], v[38:39], v[36:37]
	v_mov_b32_e32 v38, v25
	v_mov_b32_e32 v39, v21
	v_pk_fma_f32 v[36:37], v[38:39], v[38:39], v[36:37]
	v_ashrrev_i32_e32 v73, 31, v72
	v_add_f32_e32 v34, v34, v36
	v_add_f32_e32 v34, v34, v37
	s_nop 1
	v_add_f32_dpp v34, v34, v34 quad_perm:[1,0,3,2] row_mask:0xf bank_mask:0xf bound_ctrl:1
	s_nop 1
	v_add_f32_dpp v34, v34, v34 quad_perm:[2,3,0,1] row_mask:0xf bank_mask:0xf bound_ctrl:1
	s_nop 1
	v_add_f32_dpp v34, v34, v34 row_half_mirror row_mask:0xf bank_mask:0xf bound_ctrl:1
	s_nop 1
	v_add_f32_dpp v34, v34, v34 row_mirror row_mask:0xf bank_mask:0xf bound_ctrl:1
	s_nop 0
	v_readlane_b32 s16, v34, 16
	v_readlane_b32 s17, v34, 48
	v_readlane_b32 s14, v34, 0
	v_readlane_b32 s15, v34, 32
	v_mov_b32_e32 v34, s16
	v_mov_b32_e32 v35, s17
	v_pk_add_f32 v[34:35], s[14:15], v[34:35]
	s_nop 0
	v_add_f32_e32 v34, v34, v35
	v_fmamk_f32 v34, v34, 0x3a800000, v78
	v_mul_f32_e32 v35, 0x4b800000, v34
	v_cmp_gt_f32_e32 vcc, s12, v34
	s_nop 1
	v_cndmask_b32_e32 v34, v34, v35, vcc
	v_rsq_f32_e32 v34, v34
	s_nop 0
	v_mul_f32_e32 v35, 0x45800000, v34
	v_cndmask_b32_e32 v34, v34, v35, vcc
	v_mul_f32_e32 v18, v18, v34
	v_mul_f32_e32 v35, v14, v18
	v_mul_f32_e32 v18, v19, v34
	v_mul_f32_e32 v26, v26, v34
	v_mul_f32_e32 v27, v27, v34
	v_mul_f32_e32 v36, v15, v18
	v_mul_f32_e32 v18, v20, v34
	v_mul_f32_e32 v30, v30, v34
	v_mul_f32_e32 v31, v31, v34
	v_mul_f32_e32 v32, v32, v34
	v_mul_f32_e32 v33, v33, v34
	v_mul_f32_e32 v26, v6, v26
	v_mul_f32_e32 v27, v7, v27
	v_mul_f32_e32 v37, v16, v18
	v_mul_f32_e32 v18, v21, v34
	v_mul_f32_e32 v30, v2, v30
	v_mul_f32_e32 v31, v3, v31
	v_mul_f32_e32 v32, v4, v32
	v_mul_f32_e32 v33, v5, v33
	v_mul_f32_e32 v28, v28, v34
	v_mul_f32_e32 v29, v29, v34
	v_mul_f32_e32 v22, v22, v34
	v_mul_f32_e32 v23, v23, v34
	v_mul_f32_e32 v24, v24, v34
	v_mul_f32_e32 v25, v25, v34
	v_mul_f32_e32 v34, v17, v18
	v_cvt_pk_bf16_f32 v18, v30, v31
	v_cvt_pk_bf16_f32 v19, v32, v33
	v_cvt_pk_bf16_f32 v20, v26, v27
	v_lshlrev_b64 v[26:27], 11, v[72:73]
	v_mul_f32_e32 v28, v8, v28
	v_mul_f32_e32 v29, v9, v29
	v_mul_f32_e32 v22, v10, v22
	v_mul_f32_e32 v23, v11, v23
	v_mul_f32_e32 v24, v12, v24
	v_mul_f32_e32 v25, v13, v25
	v_cvt_pk_bf16_f32 v21, v28, v29
	v_lshl_add_u64 v[26:27], v[66:67], 0, v[26:27]
	v_cvt_pk_bf16_f32 v22, v22, v23
	v_cvt_pk_bf16_f32 v23, v24, v25
	v_cvt_pk_bf16_f32 v24, v35, v36
	v_cvt_pk_bf16_f32 v25, v37, v34
	global_store_dwordx4 v[26:27], v[18:21], off
	global_store_dwordx4 v[26:27], v[22:25], off offset:16
	s_branch .LBB0_7
